# v8 + P5/P9 residual epilogues: rolling prefetch of base loads 4 row-groups (16 loads) ahead via one running address pair
# speedup vs baseline: 1.0283x; 1.0081x over previous
; __device__ __forceinline__ unsigned pk2(float lo, float hi) { f32x2_t v = {lo, hi}; bf16x2_t b = __builtin_convertvector(v, bf16x2_t); return __builtin_bit_cast(unsigned, b); }
;     __device__ __forceinline__ void operator()(const f32x4 (&acc)[2][2][4][2], const Unit& u, int wr, int wc, int fr, int fq) const {
;     ...
;             for (int m = 0; m < 4; ++m) { const int row = row0 + ai * HALF + m * 16;
;                 const float* bp = base + (size_t)row * D + col0; float* op = out + (size_t)row * D + col0; bf16_t* xp = xb + (size_t)row * D + col0;
;                 float ss = 0.f;
; #pragma unroll
;                 for (int bj = 0; bj < 2; ++bj)
; #pragma unroll
;                     for (int n = 0; n < 2; ++n) { const f32x4 b = *(const f32x4*)(bp + bj * HALF + n * 16); const f32x4 x = b + acc[ai][bj][m][n]; *(f32x4*)(op + bj * HALF + n * 16) = x;
;                         u32x2 w; w.x = pk2(x.x, x.y); w.y = pk2(x.z, x.w); *(u32x2*)(xp + bj * HALF + n * 16) = w; ss += (x.x * x.x + x.y * x.y) + (x.z * x.z + x.w * x.w); }
;                 ss += __shfl_xor(ss, 16); ss += __shfl_xor(ss, 32);
;                 if (fq == 0) sred[wc * 256 + ai * HALF + wr * 64 + m * 16 + fr] = ss; }
.LBB0_521:
	s_lshl_b32 s15, s52, 8
	v_add_u32_e32 v142, s15, v146
	v_lshl_or_b32 v140, s14, 8, v148
	v_ashrrev_i32_e32 v143, 31, v142
	v_ashrrev_i32_e32 v141, 31, v140
	v_lshlrev_b64 v[160:161], 13, v[142:143]
	v_lshl_add_u64 v[156:157], s[12:13], 0, v[160:161]
	v_lshlrev_b64 v[144:145], 2, v[140:141]
	v_lshl_add_u64 v[162:163], v[156:157], 0, v[144:145]
	v_mov_b32_e32 v198, v162
	v_mov_b32_e32 v199, v163
	global_load_dwordx4 v[210:213], v[198:199], off
	global_load_dwordx4 v[214:217], v[198:199], off offset:64
	global_load_dwordx4 v[218:221], v[198:199], off offset:512
	global_load_dwordx4 v[222:225], v[198:199], off offset:576
	s_mov_b32 s100, 0x20000
	s_mov_b32 s101, 0
	v_lshl_add_u64 v[198:199], v[198:199], 0, s[100:101]
	global_load_dwordx4 v[226:229], v[198:199], off
	global_load_dwordx4 v[230:233], v[198:199], off offset:64
	global_load_dwordx4 v[234:237], v[198:199], off offset:512
	global_load_dwordx4 v[238:241], v[198:199], off offset:576
	s_mov_b32 s100, 0x20000
	s_mov_b32 s101, 0
	v_lshl_add_u64 v[198:199], v[198:199], 0, s[100:101]
	global_load_dwordx4 v[242:245], v[198:199], off
	global_load_dwordx4 v[246:249], v[198:199], off offset:64
	global_load_dwordx4 v[250:253], v[198:199], off offset:512
	global_load_dwordx4 v[168:171], v[198:199], off offset:576
	s_mov_b32 s100, 0x20000
	s_mov_b32 s101, 0
	v_lshl_add_u64 v[198:199], v[198:199], 0, s[100:101]
	global_load_dwordx4 v[172:175], v[198:199], off
	global_load_dwordx4 v[176:179], v[198:199], off offset:64
	global_load_dwordx4 v[180:183], v[198:199], off offset:512
	global_load_dwordx4 v[184:187], v[198:199], off offset:576
	v_lshlrev_b64 v[164:165], 12, v[142:143]
	v_lshl_add_u64 v[160:161], s[20:21], 0, v[160:161]
	v_lshl_add_u64 v[164:165], s[22:23], 0, v[164:165]
	v_lshl_add_u64 v[166:167], v[160:161], 0, v[144:145]
	v_lshl_add_u64 v[164:165], v[140:141], 1, v[164:165]
	s_waitcnt vmcnt(15)
	v_pk_add_f32 v[126:127], v[126:127], v[212:213]
	v_pk_add_f32 v[124:125], v[124:125], v[210:211]
	v_cvt_pk_bf16_f32 v157, v126, v127
	v_cvt_pk_bf16_f32 v156, v124, v125
	global_store_dwordx4 v[166:167], v[124:127], off
	global_store_dwordx2 v[164:165], v[156:157], off
	s_waitcnt vmcnt(16)
	v_pk_add_f32 v[122:123], v[122:123], v[216:217]
	v_pk_add_f32 v[120:121], v[120:121], v[214:215]
	v_cvt_pk_bf16_f32 v157, v122, v123
	v_cvt_pk_bf16_f32 v156, v120, v121
	global_store_dwordx4 v[166:167], v[120:123], off offset:64
	global_store_dwordx2 v[164:165], v[156:157], off offset:32
	s_waitcnt vmcnt(17)
	v_pk_add_f32 v[158:159], v[118:119], v[220:221]
	v_pk_add_f32 v[156:157], v[116:117], v[218:219]
	v_cvt_pk_bf16_f32 v117, v158, v159
	v_cvt_pk_bf16_f32 v116, v156, v157
	global_store_dwordx4 v[166:167], v[156:159], off offset:512
	global_store_dwordx2 v[164:165], v[116:117], off offset:256
	v_mul_f32_e32 v118, v125, v125
	v_mul_f32_e32 v119, v127, v127
	v_fmac_f32_e32 v118, v124, v124
	v_fmac_f32_e32 v119, v126, v126
	v_add_f32_e32 v118, v118, v119
	v_mul_f32_e32 v119, v121, v121
	v_mul_f32_e32 v121, v123, v123
	v_fmac_f32_e32 v119, v120, v120
	v_fmac_f32_e32 v121, v122, v122
	v_add_f32_e32 v119, v119, v121
	v_add_f32_e32 v118, v118, v119
	v_mul_f32_e32 v119, v157, v157
	v_mul_f32_e32 v120, v159, v159
	v_fmac_f32_e32 v119, v156, v156
	v_fmac_f32_e32 v120, v158, v158
	v_add_f32_e32 v119, v119, v120
	v_and_b32_e32 v117, 64, v154
	v_add_f32_e32 v122, v118, v119
	v_xor_b32_e32 v116, 16, v154
	v_add_u32_e32 v117, 64, v117
	v_cmp_lt_i32_e32 vcc, v116, v117
	s_waitcnt vmcnt(18)
	v_pk_add_f32 v[120:121], v[114:115], v[224:225]
	v_pk_add_f32 v[118:119], v[112:113], v[222:223]
	v_mul_f32_e32 v113, v121, v121
	v_mul_f32_e32 v112, v119, v119
	v_fmac_f32_e32 v112, v118, v118
	v_fmac_f32_e32 v113, v120, v120
	v_cndmask_b32_e32 v116, v154, v116, vcc
	v_add_f32_e32 v112, v112, v113
	v_lshlrev_b32_e32 v116, 2, v116
	v_add_f32_e32 v113, v122, v112
	ds_bpermute_b32 v114, v116, v113
	v_xor_b32_e32 v112, 32, v154
	v_cmp_lt_i32_e32 vcc, v112, v117
	global_store_dwordx4 v[166:167], v[118:121], off offset:576
	s_waitcnt lgkmcnt(0)
	v_add_f32_e32 v113, v113, v114
	v_cndmask_b32_e32 v112, v154, v112, vcc
	v_lshlrev_b32_e32 v112, 2, v112
	ds_bpermute_b32 v114, v112, v113
	v_cvt_pk_bf16_f32 v118, v118, v119
	v_cvt_pk_bf16_f32 v119, v120, v121
	global_store_dwordx2 v[164:165], v[118:119], off offset:288
	s_and_saveexec_b64 s[52:53], s[4:5]
	s_cbranch_execz .LBB0_523
	s_waitcnt lgkmcnt(0)
	v_add_f32_e32 v113, v113, v114
	ds_write_b32 v149, v113
; __device__ __forceinline__ unsigned pk2(float lo, float hi) { f32x2_t v = {lo, hi}; bf16x2_t b = __builtin_convertvector(v, bf16x2_t); return __builtin_bit_cast(unsigned, b); }
;     __device__ __forceinline__ void operator()(const f32x4 (&acc)[2][2][4][2], const Unit& u, int wr, int wc, int fr, int fq) const {
;     ...
;             for (int m = 0; m < 4; ++m) { const int row = row0 + ai * HALF + m * 16;
;                 const float* bp = base + (size_t)row * D + col0; float* op = out + (size_t)row * D + col0; bf16_t* xp = xb + (size_t)row * D + col0;
;                 float ss = 0.f;
; #pragma unroll
;                 for (int bj = 0; bj < 2; ++bj)
; #pragma unroll
;                     for (int n = 0; n < 2; ++n) { const f32x4 b = *(const f32x4*)(bp + bj * HALF + n * 16); const f32x4 x = b + acc[ai][bj][m][n]; *(f32x4*)(op + bj * HALF + n * 16) = x;
;                         u32x2 w; w.x = pk2(x.x, x.y); w.y = pk2(x.z, x.w); *(u32x2*)(xp + bj * HALF + n * 16) = w; ss += (x.x * x.x + x.y * x.y) + (x.z * x.z + x.w * x.w); }
;                 ss += __shfl_xor(ss, 16); ss += __shfl_xor(ss, 32);
;                 if (fq == 0) sred[wc * 256 + ai * HALF + wr * 64 + m * 16 + fr] = ss; }
.LBB0_523:
	s_or_b64 exec, exec, s[52:53]
	s_waitcnt lgkmcnt(0)
	v_or_b32_e32 v114, 16, v142
	v_ashrrev_i32_e32 v115, 31, v114
	v_lshlrev_b64 v[122:123], 13, v[114:115]
	v_lshl_add_u64 v[118:119], s[12:13], 0, v[122:123]
	v_lshl_add_u64 v[124:125], v[118:119], 0, v[144:145]
	s_mov_b32 s100, 0xa0000
	s_mov_b32 s101, 0
	v_lshl_add_u64 v[198:199], v[198:199], 0, s[100:101]
	global_load_dwordx4 v[210:213], v[198:199], off
	global_load_dwordx4 v[214:217], v[198:199], off offset:64
	global_load_dwordx4 v[218:221], v[198:199], off offset:512
	global_load_dwordx4 v[222:225], v[198:199], off offset:576
	v_lshlrev_b64 v[114:115], 12, v[114:115]
	v_lshl_add_u64 v[122:123], s[20:21], 0, v[122:123]
	v_lshl_add_u64 v[114:115], s[22:23], 0, v[114:115]
	v_lshl_add_u64 v[122:123], v[122:123], 0, v[144:145]
	v_lshl_add_u64 v[114:115], v[140:141], 1, v[114:115]
	s_waitcnt vmcnt(23)
	v_pk_add_f32 v[110:111], v[110:111], v[228:229]
	v_pk_add_f32 v[108:109], v[108:109], v[226:227]
	v_cvt_pk_bf16_f32 v119, v110, v111
	v_cvt_pk_bf16_f32 v118, v108, v109
	global_store_dwordx4 v[122:123], v[108:111], off
	global_store_dwordx2 v[114:115], v[118:119], off
	s_nop 0
	v_mul_f32_e32 v109, v109, v109
	v_mul_f32_e32 v111, v111, v111
	v_fmac_f32_e32 v109, v108, v108
	v_fmac_f32_e32 v111, v110, v110
	v_add_f32_e32 v108, v109, v111
	s_waitcnt vmcnt(24)
	v_pk_add_f32 v[106:107], v[106:107], v[232:233]
	v_pk_add_f32 v[104:105], v[104:105], v[230:231]
	v_cvt_pk_bf16_f32 v119, v106, v107
	v_cvt_pk_bf16_f32 v118, v104, v105
	global_store_dwordx4 v[122:123], v[104:107], off offset:64
	global_store_dwordx2 v[114:115], v[118:119], off offset:32
	s_nop 0
	v_mul_f32_e32 v105, v105, v105
	v_mul_f32_e32 v107, v107, v107
	v_fmac_f32_e32 v105, v104, v104
	v_fmac_f32_e32 v107, v106, v106
	v_add_f32_e32 v104, v105, v107
	v_add_f32_e32 v104, v108, v104
	s_waitcnt vmcnt(25)
	v_pk_add_f32 v[102:103], v[102:103], v[236:237]
	v_pk_add_f32 v[100:101], v[100:101], v[234:235]
	v_cvt_pk_bf16_f32 v119, v102, v103
	v_cvt_pk_bf16_f32 v118, v100, v101
	global_store_dwordx4 v[122:123], v[100:103], off offset:512
	global_store_dwordx2 v[114:115], v[118:119], off offset:256
	s_nop 0
	v_mul_f32_e32 v101, v101, v101
	v_mul_f32_e32 v103, v103, v103
	v_fmac_f32_e32 v101, v100, v100
	v_fmac_f32_e32 v103, v102, v102
	v_add_f32_e32 v100, v101, v103
	v_add_f32_e32 v102, v104, v100
	s_waitcnt vmcnt(26)
	v_pk_add_f32 v[100:101], v[98:99], v[240:241]
	v_pk_add_f32 v[98:99], v[96:97], v[238:239]
	v_mul_f32_e32 v97, v101, v101
	v_mul_f32_e32 v96, v99, v99
	v_fmac_f32_e32 v96, v98, v98
	v_fmac_f32_e32 v97, v100, v100
	v_add_f32_e32 v96, v96, v97
	v_add_f32_e32 v96, v102, v96
	ds_bpermute_b32 v97, v116, v96
	global_store_dwordx4 v[122:123], v[98:101], off offset:576
	s_waitcnt lgkmcnt(0)
	v_add_f32_e32 v96, v96, v97
	ds_bpermute_b32 v97, v112, v96
	v_cvt_pk_bf16_f32 v98, v98, v99
	v_cvt_pk_bf16_f32 v99, v100, v101
	global_store_dwordx2 v[114:115], v[98:99], off offset:288
	s_and_saveexec_b64 s[52:53], s[4:5]
	s_cbranch_execz .LBB0_525
	s_waitcnt lgkmcnt(0)
	v_add_f32_e32 v96, v96, v97
	ds_write_b32 v149, v96 offset:64
.LBB0_525:
	s_or_b64 exec, exec, s[52:53]
	v_or_b32_e32 v100, 32, v142
	v_ashrrev_i32_e32 v101, 31, v100
	v_lshlrev_b64 v[102:103], 13, v[100:101]
	s_waitcnt lgkmcnt(0)
	v_lshl_add_u64 v[96:97], s[12:13], 0, v[102:103]
	v_lshl_add_u64 v[104:105], v[96:97], 0, v[144:145]
	s_mov_b32 s100, 0x20000
	s_mov_b32 s101, 0
	v_lshl_add_u64 v[198:199], v[198:199], 0, s[100:101]
	global_load_dwordx4 v[226:229], v[198:199], off
	global_load_dwordx4 v[230:233], v[198:199], off offset:64
	global_load_dwordx4 v[234:237], v[198:199], off offset:512
	global_load_dwordx4 v[238:241], v[198:199], off offset:576
	v_lshlrev_b64 v[100:101], 12, v[100:101]
	v_lshl_add_u64 v[102:103], s[20:21], 0, v[102:103]
	v_lshl_add_u64 v[100:101], s[22:23], 0, v[100:101]
	v_lshl_add_u64 v[102:103], v[102:103], 0, v[144:145]
	v_lshl_add_u64 v[100:101], v[140:141], 1, v[100:101]
	s_waitcnt vmcnt(31)
	v_pk_add_f32 v[94:95], v[94:95], v[244:245]
	v_pk_add_f32 v[92:93], v[92:93], v[242:243]
	v_cvt_pk_bf16_f32 v97, v94, v95
	v_cvt_pk_bf16_f32 v96, v92, v93
	global_store_dwordx4 v[102:103], v[92:95], off
	global_store_dwordx2 v[100:101], v[96:97], off
	s_nop 0
	v_mul_f32_e32 v93, v93, v93
	v_mul_f32_e32 v95, v95, v95
	v_fmac_f32_e32 v93, v92, v92
	v_fmac_f32_e32 v95, v94, v94
	v_add_f32_e32 v92, v93, v95
	s_waitcnt vmcnt(32)
	v_pk_add_f32 v[90:91], v[90:91], v[248:249]
	v_pk_add_f32 v[88:89], v[88:89], v[246:247]
	v_cvt_pk_bf16_f32 v97, v90, v91
	v_cvt_pk_bf16_f32 v96, v88, v89
	global_store_dwordx4 v[102:103], v[88:91], off offset:64
	global_store_dwordx2 v[100:101], v[96:97], off offset:32
	s_nop 0
	v_mul_f32_e32 v89, v89, v89
	v_mul_f32_e32 v91, v91, v91
	v_fmac_f32_e32 v89, v88, v88
	v_fmac_f32_e32 v91, v90, v90
	v_add_f32_e32 v88, v89, v91
	v_add_f32_e32 v88, v92, v88
	s_waitcnt vmcnt(33)
	v_pk_add_f32 v[86:87], v[86:87], v[252:253]
	v_pk_add_f32 v[84:85], v[84:85], v[250:251]
	v_cvt_pk_bf16_f32 v97, v86, v87
	v_cvt_pk_bf16_f32 v96, v84, v85
	global_store_dwordx4 v[102:103], v[84:87], off offset:512
	global_store_dwordx2 v[100:101], v[96:97], off offset:256
	s_nop 0
	v_mul_f32_e32 v85, v85, v85
	v_mul_f32_e32 v87, v87, v87
	v_fmac_f32_e32 v85, v84, v84
	v_fmac_f32_e32 v87, v86, v86
	v_add_f32_e32 v84, v85, v87
	v_add_f32_e32 v86, v88, v84
	s_waitcnt vmcnt(34)
	v_pk_add_f32 v[84:85], v[82:83], v[170:171]
	v_pk_add_f32 v[82:83], v[80:81], v[168:169]
	v_mul_f32_e32 v81, v85, v85
	v_mul_f32_e32 v80, v83, v83
	v_fmac_f32_e32 v80, v82, v82
	v_fmac_f32_e32 v81, v84, v84
	v_add_f32_e32 v80, v80, v81
	v_add_f32_e32 v80, v86, v80
	ds_bpermute_b32 v81, v116, v80
	global_store_dwordx4 v[102:103], v[82:85], off offset:576
	s_waitcnt lgkmcnt(0)
	v_add_f32_e32 v80, v80, v81
	ds_bpermute_b32 v81, v112, v80
	v_cvt_pk_bf16_f32 v82, v82, v83
	v_cvt_pk_bf16_f32 v83, v84, v85
	global_store_dwordx2 v[100:101], v[82:83], off offset:288
	s_and_saveexec_b64 s[52:53], s[4:5]
	s_cbranch_execz .LBB0_527
	s_waitcnt lgkmcnt(0)
	v_add_f32_e32 v80, v80, v81
	ds_write_b32 v149, v80 offset:128
; __device__ __forceinline__ unsigned pk2(float lo, float hi) { f32x2_t v = {lo, hi}; bf16x2_t b = __builtin_convertvector(v, bf16x2_t); return __builtin_bit_cast(unsigned, b); }
;     __device__ __forceinline__ void operator()(const f32x4 (&acc)[2][2][4][2], const Unit& u, int wr, int wc, int fr, int fq) const {
;     ...
;             for (int m = 0; m < 4; ++m) { const int row = row0 + ai * HALF + m * 16;
;                 const float* bp = base + (size_t)row * D + col0; float* op = out + (size_t)row * D + col0; bf16_t* xp = xb + (size_t)row * D + col0;
;                 float ss = 0.f;
; #pragma unroll
;                 for (int bj = 0; bj < 2; ++bj)
; #pragma unroll
;                     for (int n = 0; n < 2; ++n) { const f32x4 b = *(const f32x4*)(bp + bj * HALF + n * 16); const f32x4 x = b + acc[ai][bj][m][n]; *(f32x4*)(op + bj * HALF + n * 16) = x;
;                         u32x2 w; w.x = pk2(x.x, x.y); w.y = pk2(x.z, x.w); *(u32x2*)(xp + bj * HALF + n * 16) = w; ss += (x.x * x.x + x.y * x.y) + (x.z * x.z + x.w * x.w); }
;                 ss += __shfl_xor(ss, 16); ss += __shfl_xor(ss, 32);
;                 if (fq == 0) sred[wc * 256 + ai * HALF + wr * 64 + m * 16 + fr] = ss; }
.LBB0_527:
	s_or_b64 exec, exec, s[52:53]
	v_or_b32_e32 v84, 48, v142
	v_ashrrev_i32_e32 v85, 31, v84
	v_lshlrev_b64 v[86:87], 13, v[84:85]
	s_waitcnt lgkmcnt(0)
	v_lshl_add_u64 v[80:81], s[12:13], 0, v[86:87]
	v_lshl_add_u64 v[88:89], v[80:81], 0, v[144:145]
	s_mov_b32 s100, 0x20000
	s_mov_b32 s101, 0
	v_lshl_add_u64 v[198:199], v[198:199], 0, s[100:101]
	global_load_dwordx4 v[242:245], v[198:199], off
	global_load_dwordx4 v[246:249], v[198:199], off offset:64
	global_load_dwordx4 v[250:253], v[198:199], off offset:512
	global_load_dwordx4 v[168:171], v[198:199], off offset:576
	v_lshlrev_b64 v[84:85], 12, v[84:85]
	v_lshl_add_u64 v[86:87], s[20:21], 0, v[86:87]
	v_lshl_add_u64 v[84:85], s[22:23], 0, v[84:85]
	v_lshl_add_u64 v[86:87], v[86:87], 0, v[144:145]
	v_lshl_add_u64 v[84:85], v[140:141], 1, v[84:85]
	s_waitcnt vmcnt(39)
	v_pk_add_f32 v[78:79], v[78:79], v[174:175]
	v_pk_add_f32 v[76:77], v[76:77], v[172:173]
	v_cvt_pk_bf16_f32 v81, v78, v79
	v_cvt_pk_bf16_f32 v80, v76, v77
	global_store_dwordx4 v[86:87], v[76:79], off
	global_store_dwordx2 v[84:85], v[80:81], off
	s_nop 0
	v_mul_f32_e32 v77, v77, v77
	v_mul_f32_e32 v79, v79, v79
	v_fmac_f32_e32 v77, v76, v76
	v_fmac_f32_e32 v79, v78, v78
	v_add_f32_e32 v76, v77, v79
	s_waitcnt vmcnt(40)
	v_pk_add_f32 v[74:75], v[74:75], v[178:179]
	v_pk_add_f32 v[72:73], v[72:73], v[176:177]
	v_cvt_pk_bf16_f32 v81, v74, v75
	v_cvt_pk_bf16_f32 v80, v72, v73
	global_store_dwordx4 v[86:87], v[72:75], off offset:64
	global_store_dwordx2 v[84:85], v[80:81], off offset:32
	s_nop 0
	v_mul_f32_e32 v73, v73, v73
	v_mul_f32_e32 v75, v75, v75
	v_fmac_f32_e32 v73, v72, v72
	v_fmac_f32_e32 v75, v74, v74
	v_add_f32_e32 v72, v73, v75
	v_add_f32_e32 v72, v76, v72
	s_waitcnt vmcnt(41)
	v_pk_add_f32 v[70:71], v[70:71], v[182:183]
	v_pk_add_f32 v[68:69], v[68:69], v[180:181]
	v_cvt_pk_bf16_f32 v81, v70, v71
	v_cvt_pk_bf16_f32 v80, v68, v69
	global_store_dwordx4 v[86:87], v[68:71], off offset:512
	global_store_dwordx2 v[84:85], v[80:81], off offset:256
	s_nop 0
	v_mul_f32_e32 v69, v69, v69
	v_mul_f32_e32 v71, v71, v71
	v_fmac_f32_e32 v69, v68, v68
	v_fmac_f32_e32 v71, v70, v70
	v_add_f32_e32 v68, v69, v71
	v_add_f32_e32 v70, v72, v68
	s_waitcnt vmcnt(42)
	v_pk_add_f32 v[68:69], v[66:67], v[186:187]
	v_pk_add_f32 v[66:67], v[64:65], v[184:185]
	v_mul_f32_e32 v65, v69, v69
	v_mul_f32_e32 v64, v67, v67
	v_fmac_f32_e32 v64, v66, v66
	v_fmac_f32_e32 v65, v68, v68
	v_add_f32_e32 v64, v64, v65
	v_add_f32_e32 v64, v70, v64
	ds_bpermute_b32 v65, v116, v64
	global_store_dwordx4 v[86:87], v[66:69], off offset:576
	s_waitcnt lgkmcnt(0)
	v_add_f32_e32 v64, v64, v65
	ds_bpermute_b32 v65, v112, v64
	v_cvt_pk_bf16_f32 v66, v66, v67
	v_cvt_pk_bf16_f32 v67, v68, v69
	global_store_dwordx2 v[84:85], v[66:67], off offset:288
	s_and_saveexec_b64 s[52:53], s[4:5]
	s_cbranch_execz .LBB0_529
	s_waitcnt lgkmcnt(0)
	v_add_f32_e32 v64, v64, v65
	ds_write_b32 v149, v64 offset:192
.LBB0_529:
	s_or_b64 exec, exec, s[52:53]
	v_add_u32_e32 v68, 0x80, v142
	v_ashrrev_i32_e32 v69, 31, v68
	v_lshlrev_b64 v[70:71], 13, v[68:69]
	s_waitcnt lgkmcnt(0)
	v_lshl_add_u64 v[64:65], s[12:13], 0, v[70:71]
	v_lshl_add_u64 v[72:73], v[64:65], 0, v[144:145]
	s_mov_b32 s100, 0x20000
	s_mov_b32 s101, 0
	v_lshl_add_u64 v[198:199], v[198:199], 0, s[100:101]
	global_load_dwordx4 v[172:175], v[198:199], off
	global_load_dwordx4 v[176:179], v[198:199], off offset:64
	global_load_dwordx4 v[180:183], v[198:199], off offset:512
	global_load_dwordx4 v[184:187], v[198:199], off offset:576
	v_lshlrev_b64 v[68:69], 12, v[68:69]
	v_lshl_add_u64 v[70:71], s[20:21], 0, v[70:71]
	v_lshl_add_u64 v[68:69], s[22:23], 0, v[68:69]
	v_lshl_add_u64 v[70:71], v[70:71], 0, v[144:145]
	v_lshl_add_u64 v[68:69], v[140:141], 1, v[68:69]
	s_waitcnt vmcnt(39)
	v_pk_add_f32 v[62:63], v[62:63], v[212:213]
	v_pk_add_f32 v[60:61], v[60:61], v[210:211]
	v_cvt_pk_bf16_f32 v65, v62, v63
	v_cvt_pk_bf16_f32 v64, v60, v61
	global_store_dwordx4 v[70:71], v[60:63], off
	global_store_dwordx2 v[68:69], v[64:65], off
	s_nop 0
	v_mul_f32_e32 v61, v61, v61
	v_mul_f32_e32 v63, v63, v63
	v_fmac_f32_e32 v61, v60, v60
	v_fmac_f32_e32 v63, v62, v62
	v_add_f32_e32 v60, v61, v63
	s_waitcnt vmcnt(40)
	v_pk_add_f32 v[58:59], v[58:59], v[216:217]
	v_pk_add_f32 v[56:57], v[56:57], v[214:215]
	v_cvt_pk_bf16_f32 v65, v58, v59
	v_cvt_pk_bf16_f32 v64, v56, v57
	global_store_dwordx4 v[70:71], v[56:59], off offset:64
	global_store_dwordx2 v[68:69], v[64:65], off offset:32
	s_nop 0
	v_mul_f32_e32 v57, v57, v57
	v_mul_f32_e32 v59, v59, v59
	v_fmac_f32_e32 v57, v56, v56
	v_fmac_f32_e32 v59, v58, v58
	v_add_f32_e32 v56, v57, v59
	v_add_f32_e32 v56, v60, v56
	s_waitcnt vmcnt(41)
	v_pk_add_f32 v[54:55], v[54:55], v[220:221]
	v_pk_add_f32 v[52:53], v[52:53], v[218:219]
	v_cvt_pk_bf16_f32 v65, v54, v55
	v_cvt_pk_bf16_f32 v64, v52, v53
	global_store_dwordx4 v[70:71], v[52:55], off offset:512
	global_store_dwordx2 v[68:69], v[64:65], off offset:256
	s_nop 0
	v_mul_f32_e32 v53, v53, v53
	v_mul_f32_e32 v55, v55, v55
	v_fmac_f32_e32 v53, v52, v52
	v_fmac_f32_e32 v55, v54, v54
	v_add_f32_e32 v52, v53, v55
	v_add_f32_e32 v54, v56, v52
	s_waitcnt vmcnt(42)
	v_pk_add_f32 v[52:53], v[50:51], v[224:225]
	v_pk_add_f32 v[50:51], v[48:49], v[222:223]
	v_mul_f32_e32 v49, v53, v53
	v_mul_f32_e32 v48, v51, v51
	v_fmac_f32_e32 v48, v50, v50
	v_fmac_f32_e32 v49, v52, v52
	v_add_f32_e32 v48, v48, v49
	v_add_f32_e32 v48, v54, v48
	ds_bpermute_b32 v49, v116, v48
	global_store_dwordx4 v[70:71], v[50:53], off offset:576
	s_waitcnt lgkmcnt(0)
	v_add_f32_e32 v48, v48, v49
	ds_bpermute_b32 v49, v112, v48
	v_cvt_pk_bf16_f32 v50, v50, v51
	v_cvt_pk_bf16_f32 v51, v52, v53
	global_store_dwordx2 v[68:69], v[50:51], off offset:288
	s_and_saveexec_b64 s[52:53], s[4:5]
	s_cbranch_execz .LBB0_531
	s_waitcnt lgkmcnt(0)
	v_add_f32_e32 v48, v48, v49
	ds_write_b32 v149, v48 offset:512
; __device__ __forceinline__ unsigned pk2(float lo, float hi) { f32x2_t v = {lo, hi}; bf16x2_t b = __builtin_convertvector(v, bf16x2_t); return __builtin_bit_cast(unsigned, b); }
;     __device__ __forceinline__ void operator()(const f32x4 (&acc)[2][2][4][2], const Unit& u, int wr, int wc, int fr, int fq) const {
;     ...
;             for (int m = 0; m < 4; ++m) { const int row = row0 + ai * HALF + m * 16;
;                 const float* bp = base + (size_t)row * D + col0; float* op = out + (size_t)row * D + col0; bf16_t* xp = xb + (size_t)row * D + col0;
;                 float ss = 0.f;
; #pragma unroll
;                 for (int bj = 0; bj < 2; ++bj)
; #pragma unroll
;                     for (int n = 0; n < 2; ++n) { const f32x4 b = *(const f32x4*)(bp + bj * HALF + n * 16); const f32x4 x = b + acc[ai][bj][m][n]; *(f32x4*)(op + bj * HALF + n * 16) = x;
;                         u32x2 w; w.x = pk2(x.x, x.y); w.y = pk2(x.z, x.w); *(u32x2*)(xp + bj * HALF + n * 16) = w; ss += (x.x * x.x + x.y * x.y) + (x.z * x.z + x.w * x.w); }
;                 ss += __shfl_xor(ss, 16); ss += __shfl_xor(ss, 32);
;                 if (fq == 0) sred[wc * 256 + ai * HALF + wr * 64 + m * 16 + fr] = ss; }
.LBB0_531:
	s_or_b64 exec, exec, s[52:53]
	v_add_u32_e32 v52, 0x90, v142
	v_ashrrev_i32_e32 v53, 31, v52
	v_lshlrev_b64 v[54:55], 13, v[52:53]
	s_waitcnt lgkmcnt(0)
	v_lshl_add_u64 v[48:49], s[12:13], 0, v[54:55]
	v_lshl_add_u64 v[56:57], v[48:49], 0, v[144:145]
	v_lshlrev_b64 v[52:53], 12, v[52:53]
	v_lshl_add_u64 v[54:55], s[20:21], 0, v[54:55]
	v_lshl_add_u64 v[52:53], s[22:23], 0, v[52:53]
	v_lshl_add_u64 v[54:55], v[54:55], 0, v[144:145]
	v_lshl_add_u64 v[52:53], v[140:141], 1, v[52:53]
	s_waitcnt vmcnt(35)
	v_pk_add_f32 v[46:47], v[46:47], v[228:229]
	v_pk_add_f32 v[44:45], v[44:45], v[226:227]
	v_cvt_pk_bf16_f32 v49, v46, v47
	v_cvt_pk_bf16_f32 v48, v44, v45
	global_store_dwordx4 v[54:55], v[44:47], off
	global_store_dwordx2 v[52:53], v[48:49], off
	s_nop 0
	v_mul_f32_e32 v45, v45, v45
	v_mul_f32_e32 v47, v47, v47
	v_fmac_f32_e32 v45, v44, v44
	v_fmac_f32_e32 v47, v46, v46
	v_add_f32_e32 v44, v45, v47
	s_waitcnt vmcnt(36)
	v_pk_add_f32 v[42:43], v[42:43], v[232:233]
	v_pk_add_f32 v[40:41], v[40:41], v[230:231]
	v_cvt_pk_bf16_f32 v49, v42, v43
	v_cvt_pk_bf16_f32 v48, v40, v41
	global_store_dwordx4 v[54:55], v[40:43], off offset:64
	global_store_dwordx2 v[52:53], v[48:49], off offset:32
	s_nop 0
	v_mul_f32_e32 v41, v41, v41
	v_mul_f32_e32 v43, v43, v43
	v_fmac_f32_e32 v41, v40, v40
	v_fmac_f32_e32 v43, v42, v42
	v_add_f32_e32 v40, v41, v43
	v_add_f32_e32 v40, v44, v40
	s_waitcnt vmcnt(37)
	v_pk_add_f32 v[38:39], v[38:39], v[236:237]
	v_pk_add_f32 v[36:37], v[36:37], v[234:235]
	v_cvt_pk_bf16_f32 v49, v38, v39
	v_cvt_pk_bf16_f32 v48, v36, v37
	global_store_dwordx4 v[54:55], v[36:39], off offset:512
	global_store_dwordx2 v[52:53], v[48:49], off offset:256
	s_nop 0
	v_mul_f32_e32 v37, v37, v37
	v_mul_f32_e32 v39, v39, v39
	v_fmac_f32_e32 v37, v36, v36
	v_fmac_f32_e32 v39, v38, v38
	v_add_f32_e32 v36, v37, v39
	v_add_f32_e32 v38, v40, v36
	s_waitcnt vmcnt(38)
	v_pk_add_f32 v[36:37], v[34:35], v[240:241]
	v_pk_add_f32 v[34:35], v[32:33], v[238:239]
	v_mul_f32_e32 v33, v37, v37
	v_mul_f32_e32 v32, v35, v35
	v_fmac_f32_e32 v32, v34, v34
	v_fmac_f32_e32 v33, v36, v36
	v_add_f32_e32 v32, v32, v33
	v_add_f32_e32 v32, v38, v32
	ds_bpermute_b32 v33, v116, v32
	global_store_dwordx4 v[54:55], v[34:37], off offset:576
	s_waitcnt lgkmcnt(0)
	v_add_f32_e32 v32, v32, v33
	ds_bpermute_b32 v33, v112, v32
	v_cvt_pk_bf16_f32 v34, v34, v35
	v_cvt_pk_bf16_f32 v35, v36, v37
	global_store_dwordx2 v[52:53], v[34:35], off offset:288
	s_and_saveexec_b64 s[52:53], s[4:5]
	s_cbranch_execz .LBB0_533
	s_waitcnt lgkmcnt(0)
	v_add_f32_e32 v32, v32, v33
	ds_write_b32 v149, v32 offset:576
; __device__ __forceinline__ unsigned pk2(float lo, float hi) { f32x2_t v = {lo, hi}; bf16x2_t b = __builtin_convertvector(v, bf16x2_t); return __builtin_bit_cast(unsigned, b); }
;     __device__ __forceinline__ void operator()(const f32x4 (&acc)[2][2][4][2], const Unit& u, int wr, int wc, int fr, int fq) const {
;     ...
;             for (int m = 0; m < 4; ++m) { const int row = row0 + ai * HALF + m * 16;
;                 const float* bp = base + (size_t)row * D + col0; float* op = out + (size_t)row * D + col0; bf16_t* xp = xb + (size_t)row * D + col0;
;                 float ss = 0.f;
; #pragma unroll
;                 for (int bj = 0; bj < 2; ++bj)
; #pragma unroll
;                     for (int n = 0; n < 2; ++n) { const f32x4 b = *(const f32x4*)(bp + bj * HALF + n * 16); const f32x4 x = b + acc[ai][bj][m][n]; *(f32x4*)(op + bj * HALF + n * 16) = x;
;                         u32x2 w; w.x = pk2(x.x, x.y); w.y = pk2(x.z, x.w); *(u32x2*)(xp + bj * HALF + n * 16) = w; ss += (x.x * x.x + x.y * x.y) + (x.z * x.z + x.w * x.w); }
;                 ss += __shfl_xor(ss, 16); ss += __shfl_xor(ss, 32);
;                 if (fq == 0) sred[wc * 256 + ai * HALF + wr * 64 + m * 16 + fr] = ss; }
.LBB0_533:
	s_or_b64 exec, exec, s[52:53]
	v_add_u32_e32 v36, 0xa0, v142
	v_ashrrev_i32_e32 v37, 31, v36
	v_lshlrev_b64 v[38:39], 13, v[36:37]
	s_waitcnt lgkmcnt(0)
	v_lshl_add_u64 v[32:33], s[12:13], 0, v[38:39]
	v_lshl_add_u64 v[40:41], v[32:33], 0, v[144:145]
	v_lshlrev_b64 v[36:37], 12, v[36:37]
	v_lshl_add_u64 v[38:39], s[20:21], 0, v[38:39]
	v_lshl_add_u64 v[36:37], s[22:23], 0, v[36:37]
	v_lshl_add_u64 v[38:39], v[38:39], 0, v[144:145]
	v_lshl_add_u64 v[36:37], v[140:141], 1, v[36:37]
	s_waitcnt vmcnt(31)
	v_pk_add_f32 v[30:31], v[30:31], v[244:245]
	v_pk_add_f32 v[28:29], v[28:29], v[242:243]
	v_cvt_pk_bf16_f32 v33, v30, v31
	v_cvt_pk_bf16_f32 v32, v28, v29
	global_store_dwordx4 v[38:39], v[28:31], off
	global_store_dwordx2 v[36:37], v[32:33], off
	s_nop 0
	v_mul_f32_e32 v29, v29, v29
	v_mul_f32_e32 v31, v31, v31
	v_fmac_f32_e32 v29, v28, v28
	v_fmac_f32_e32 v31, v30, v30
	v_add_f32_e32 v28, v29, v31
	s_waitcnt vmcnt(32)
	v_pk_add_f32 v[26:27], v[26:27], v[248:249]
	v_pk_add_f32 v[24:25], v[24:25], v[246:247]
	v_cvt_pk_bf16_f32 v33, v26, v27
	v_cvt_pk_bf16_f32 v32, v24, v25
	global_store_dwordx4 v[38:39], v[24:27], off offset:64
	global_store_dwordx2 v[36:37], v[32:33], off offset:32
	s_nop 0
	v_mul_f32_e32 v25, v25, v25
	v_mul_f32_e32 v27, v27, v27
	v_fmac_f32_e32 v25, v24, v24
	v_fmac_f32_e32 v27, v26, v26
	v_add_f32_e32 v24, v25, v27
	v_add_f32_e32 v24, v28, v24
	s_waitcnt vmcnt(33)
	v_pk_add_f32 v[22:23], v[22:23], v[252:253]
	v_pk_add_f32 v[20:21], v[20:21], v[250:251]
	v_cvt_pk_bf16_f32 v33, v22, v23
	v_cvt_pk_bf16_f32 v32, v20, v21
	global_store_dwordx4 v[38:39], v[20:23], off offset:512
	global_store_dwordx2 v[36:37], v[32:33], off offset:256
	s_nop 0
	v_mul_f32_e32 v21, v21, v21
	v_mul_f32_e32 v23, v23, v23
	v_fmac_f32_e32 v21, v20, v20
	v_fmac_f32_e32 v23, v22, v22
	v_add_f32_e32 v20, v21, v23
	v_add_f32_e32 v22, v24, v20
	s_waitcnt vmcnt(34)
	v_pk_add_f32 v[20:21], v[18:19], v[170:171]
	v_pk_add_f32 v[18:19], v[16:17], v[168:169]
	v_mul_f32_e32 v17, v21, v21
	v_mul_f32_e32 v16, v19, v19
	v_fmac_f32_e32 v16, v18, v18
	v_fmac_f32_e32 v17, v20, v20
	v_add_f32_e32 v16, v16, v17
	v_add_f32_e32 v16, v22, v16
	ds_bpermute_b32 v17, v116, v16
	global_store_dwordx4 v[38:39], v[18:21], off offset:576
	s_waitcnt lgkmcnt(0)
	v_add_f32_e32 v16, v16, v17
	ds_bpermute_b32 v17, v112, v16
	v_cvt_pk_bf16_f32 v18, v18, v19
	v_cvt_pk_bf16_f32 v19, v20, v21
	global_store_dwordx2 v[36:37], v[18:19], off offset:288
	s_and_saveexec_b64 s[52:53], s[4:5]
	s_cbranch_execz .LBB0_535
	s_waitcnt lgkmcnt(0)
	v_add_f32_e32 v16, v16, v17
	ds_write_b32 v149, v16 offset:640
.LBB0_535:
	s_or_b64 exec, exec, s[52:53]
	v_add_u32_e32 v20, 0xb0, v142
	v_ashrrev_i32_e32 v21, 31, v20
	v_lshlrev_b64 v[22:23], 13, v[20:21]
	s_waitcnt lgkmcnt(0)
	v_lshl_add_u64 v[16:17], s[12:13], 0, v[22:23]
	v_lshl_add_u64 v[24:25], v[16:17], 0, v[144:145]
	v_lshlrev_b64 v[20:21], 12, v[20:21]
	v_lshl_add_u64 v[22:23], s[20:21], 0, v[22:23]
	v_lshl_add_u64 v[20:21], s[22:23], 0, v[20:21]
	v_lshl_add_u64 v[22:23], v[22:23], 0, v[144:145]
	v_lshl_add_u64 v[20:21], v[140:141], 1, v[20:21]
	s_waitcnt vmcnt(27)
	v_pk_add_f32 v[14:15], v[14:15], v[174:175]
	v_pk_add_f32 v[12:13], v[12:13], v[172:173]
	v_cvt_pk_bf16_f32 v17, v14, v15
	v_cvt_pk_bf16_f32 v16, v12, v13
	global_store_dwordx4 v[22:23], v[12:15], off
	global_store_dwordx2 v[20:21], v[16:17], off
	s_nop 0
	v_mul_f32_e32 v13, v13, v13
	v_mul_f32_e32 v15, v15, v15
	v_fmac_f32_e32 v13, v12, v12
	v_fmac_f32_e32 v15, v14, v14
	v_add_f32_e32 v12, v13, v15
	s_waitcnt vmcnt(28)
	v_pk_add_f32 v[10:11], v[10:11], v[178:179]
	v_pk_add_f32 v[8:9], v[8:9], v[176:177]
	v_cvt_pk_bf16_f32 v17, v10, v11
	v_cvt_pk_bf16_f32 v16, v8, v9
	global_store_dwordx4 v[22:23], v[8:11], off offset:64
	global_store_dwordx2 v[20:21], v[16:17], off offset:32
	s_nop 0
	v_mul_f32_e32 v9, v9, v9
	v_mul_f32_e32 v11, v11, v11
	v_fmac_f32_e32 v9, v8, v8
	v_fmac_f32_e32 v11, v10, v10
	v_add_f32_e32 v8, v9, v11
	v_add_f32_e32 v8, v12, v8
	s_waitcnt vmcnt(29)
	v_pk_add_f32 v[6:7], v[6:7], v[182:183]
	v_pk_add_f32 v[4:5], v[4:5], v[180:181]
	v_cvt_pk_bf16_f32 v17, v6, v7
	v_cvt_pk_bf16_f32 v16, v4, v5
	global_store_dwordx4 v[22:23], v[4:7], off offset:512
	global_store_dwordx2 v[20:21], v[16:17], off offset:256
	s_nop 0
	v_mul_f32_e32 v5, v5, v5
	v_mul_f32_e32 v7, v7, v7
	v_fmac_f32_e32 v5, v4, v4
	v_fmac_f32_e32 v7, v6, v6
	v_add_f32_e32 v4, v5, v7
	v_add_f32_e32 v6, v8, v4
	s_waitcnt vmcnt(30)
	v_pk_add_f32 v[4:5], v[2:3], v[186:187]
	v_pk_add_f32 v[2:3], v[0:1], v[184:185]
	v_mul_f32_e32 v1, v5, v5
	v_mul_f32_e32 v0, v3, v3
	v_fmac_f32_e32 v0, v2, v2
	v_fmac_f32_e32 v1, v4, v4
	v_add_f32_e32 v0, v0, v1
	v_add_f32_e32 v0, v6, v0
	ds_bpermute_b32 v1, v116, v0
	global_store_dwordx4 v[22:23], v[2:5], off offset:576
	s_waitcnt lgkmcnt(0)
	v_add_f32_e32 v0, v0, v1
	ds_bpermute_b32 v1, v112, v0
	v_cvt_pk_bf16_f32 v2, v2, v3
	v_cvt_pk_bf16_f32 v3, v4, v5
	global_store_dwordx2 v[20:21], v[2:3], off offset:288
	s_and_saveexec_b64 s[52:53], s[4:5]
	s_cbranch_execz .LBB0_537
	s_waitcnt lgkmcnt(0)
	v_add_f32_e32 v0, v0, v1
	ds_write_b32 v149, v0 offset:704

; __device__ __forceinline__ unsigned pk2(float lo, float hi) { f32x2_t v = {lo, hi}; bf16x2_t b = __builtin_convertvector(v, bf16x2_t); return __builtin_bit_cast(unsigned, b); }
;     __device__ __forceinline__ void operator()(const f32x4 (&acc)[2][2][4][2], const Unit& u, int wr, int wc, int fr, int fq) const {
;     ...
;             for (int m = 0; m < 4; ++m) { const int row = row0 + ai * HALF + m * 16;
;                 const float* bp = base + (size_t)row * D + col0; float* op = out + (size_t)row * D + col0; bf16_t* xp = xb + (size_t)row * D + col0;
;                 float ss = 0.f;
; #pragma unroll
;                 for (int bj = 0; bj < 2; ++bj)
; #pragma unroll
;                     for (int n = 0; n < 2; ++n) { const f32x4 b = *(const f32x4*)(bp + bj * HALF + n * 16); const f32x4 x = b + acc[ai][bj][m][n]; *(f32x4*)(op + bj * HALF + n * 16) = x;
;                         u32x2 w; w.x = pk2(x.x, x.y); w.y = pk2(x.z, x.w); *(u32x2*)(xp + bj * HALF + n * 16) = w; ss += (x.x * x.x + x.y * x.y) + (x.z * x.z + x.w * x.w); }
;                 ss += __shfl_xor(ss, 16); ss += __shfl_xor(ss, 32);
;                 if (fq == 0) sred[wc * 256 + ai * HALF + wr * 64 + m * 16 + fr] = ss; }
.LBB0_728:
	s_lshl_b32 s11, s50, 8
	v_add_u32_e32 v142, s11, v144
	v_ashrrev_i32_e32 v143, 31, v142
	v_lshl_or_b32 v140, s10, 8, v146
	v_lshlrev_b64 v[154:155], 13, v[142:143]
	v_ashrrev_i32_e32 v141, 31, v140
	v_lshl_add_u64 v[154:155], s[14:15], 0, v[154:155]
	v_lshl_add_u64 v[162:163], v[140:141], 2, v[154:155]
	v_mov_b32_e32 v198, v162
	v_mov_b32_e32 v199, v163
	global_load_dwordx4 v[210:213], v[198:199], off
	global_load_dwordx4 v[214:217], v[198:199], off offset:64
	global_load_dwordx4 v[218:221], v[198:199], off offset:512
	global_load_dwordx4 v[222:225], v[198:199], off offset:576
	s_mov_b32 s100, 0x20000
	s_mov_b32 s101, 0
	v_lshl_add_u64 v[198:199], v[198:199], 0, s[100:101]
	global_load_dwordx4 v[226:229], v[198:199], off
	global_load_dwordx4 v[230:233], v[198:199], off offset:64
	global_load_dwordx4 v[234:237], v[198:199], off offset:512
	global_load_dwordx4 v[238:241], v[198:199], off offset:576
	s_mov_b32 s100, 0x20000
	s_mov_b32 s101, 0
	v_lshl_add_u64 v[198:199], v[198:199], 0, s[100:101]
	global_load_dwordx4 v[242:245], v[198:199], off
	global_load_dwordx4 v[246:249], v[198:199], off offset:64
	global_load_dwordx4 v[250:253], v[198:199], off offset:512
	global_load_dwordx4 v[168:171], v[198:199], off offset:576
	s_mov_b32 s100, 0x20000
	s_mov_b32 s101, 0
	v_lshl_add_u64 v[198:199], v[198:199], 0, s[100:101]
	global_load_dwordx4 v[172:175], v[198:199], off
	global_load_dwordx4 v[176:179], v[198:199], off offset:64
	global_load_dwordx4 v[180:183], v[198:199], off offset:512
	global_load_dwordx4 v[184:187], v[198:199], off offset:576
	v_lshlrev_b64 v[158:159], 12, v[142:143]
	v_lshl_add_u64 v[158:159], s[18:19], 0, v[158:159]
	v_lshl_add_u64 v[164:165], v[140:141], 1, v[158:159]
	s_waitcnt vmcnt(15)
	v_pk_add_f32 v[126:127], v[126:127], v[212:213]
	v_pk_add_f32 v[124:125], v[124:125], v[210:211]
	v_cvt_pk_bf16_f32 v155, v126, v127
	v_cvt_pk_bf16_f32 v154, v124, v125
	global_store_dwordx4 v[162:163], v[124:127], off
	global_store_dwordx2 v[164:165], v[154:155], off
	s_waitcnt vmcnt(16)
	v_pk_add_f32 v[122:123], v[122:123], v[216:217]
	v_pk_add_f32 v[120:121], v[120:121], v[214:215]
	v_cvt_pk_bf16_f32 v155, v122, v123
	v_cvt_pk_bf16_f32 v154, v120, v121
	global_store_dwordx4 v[162:163], v[120:123], off offset:64
	global_store_dwordx2 v[164:165], v[154:155], off offset:32
	s_waitcnt vmcnt(17)
	v_pk_add_f32 v[156:157], v[118:119], v[220:221]
	v_pk_add_f32 v[154:155], v[116:117], v[218:219]
	v_cvt_pk_bf16_f32 v117, v156, v157
	v_cvt_pk_bf16_f32 v116, v154, v155
	global_store_dwordx4 v[162:163], v[154:157], off offset:512
	global_store_dwordx2 v[164:165], v[116:117], off offset:256
	v_mul_f32_e32 v118, v125, v125
	v_mul_f32_e32 v119, v127, v127
	v_fmac_f32_e32 v118, v124, v124
	v_fmac_f32_e32 v119, v126, v126
	v_add_f32_e32 v118, v118, v119
	v_mul_f32_e32 v119, v121, v121
	v_mul_f32_e32 v121, v123, v123
	v_fmac_f32_e32 v119, v120, v120
	v_fmac_f32_e32 v121, v122, v122
	v_add_f32_e32 v119, v119, v121
	v_add_f32_e32 v118, v118, v119
	v_mul_f32_e32 v119, v155, v155
	v_mul_f32_e32 v120, v157, v157
	v_fmac_f32_e32 v119, v154, v154
	v_fmac_f32_e32 v120, v156, v156
	v_add_f32_e32 v119, v119, v120
	v_and_b32_e32 v117, 64, v152
	v_add_f32_e32 v122, v118, v119
	v_xor_b32_e32 v116, 16, v152
	v_add_u32_e32 v117, 64, v117
	v_cmp_lt_i32_e32 vcc, v116, v117
	s_waitcnt vmcnt(18)
	v_pk_add_f32 v[120:121], v[114:115], v[224:225]
	v_pk_add_f32 v[118:119], v[112:113], v[222:223]
	v_mul_f32_e32 v113, v121, v121
	v_mul_f32_e32 v112, v119, v119
	v_fmac_f32_e32 v112, v118, v118
	v_fmac_f32_e32 v113, v120, v120
	v_cndmask_b32_e32 v116, v152, v116, vcc
	v_add_f32_e32 v112, v112, v113
	v_lshlrev_b32_e32 v116, 2, v116
	v_add_f32_e32 v113, v122, v112
	ds_bpermute_b32 v114, v116, v113
	v_xor_b32_e32 v112, 32, v152
	v_cmp_lt_i32_e32 vcc, v112, v117
	global_store_dwordx4 v[162:163], v[118:121], off offset:576
	s_waitcnt lgkmcnt(0)
	v_add_f32_e32 v113, v113, v114
	v_cndmask_b32_e32 v112, v152, v112, vcc
	v_lshlrev_b32_e32 v112, 2, v112
	ds_bpermute_b32 v114, v112, v113
	v_cvt_pk_bf16_f32 v118, v118, v119
	v_cvt_pk_bf16_f32 v119, v120, v121
	global_store_dwordx2 v[164:165], v[118:119], off offset:288
	s_and_saveexec_b64 s[50:51], s[4:5]
	s_cbranch_execz .LBB0_730
	s_waitcnt lgkmcnt(0)
	v_add_f32_e32 v113, v113, v114
	ds_write_b32 v147, v113
; __device__ __forceinline__ unsigned pk2(float lo, float hi) { f32x2_t v = {lo, hi}; bf16x2_t b = __builtin_convertvector(v, bf16x2_t); return __builtin_bit_cast(unsigned, b); }
;     __device__ __forceinline__ void operator()(const f32x4 (&acc)[2][2][4][2], const Unit& u, int wr, int wc, int fr, int fq) const {
;     ...
;             for (int m = 0; m < 4; ++m) { const int row = row0 + ai * HALF + m * 16;
;                 const float* bp = base + (size_t)row * D + col0; float* op = out + (size_t)row * D + col0; bf16_t* xp = xb + (size_t)row * D + col0;
;                 float ss = 0.f;
; #pragma unroll
;                 for (int bj = 0; bj < 2; ++bj)
; #pragma unroll
;                     for (int n = 0; n < 2; ++n) { const f32x4 b = *(const f32x4*)(bp + bj * HALF + n * 16); const f32x4 x = b + acc[ai][bj][m][n]; *(f32x4*)(op + bj * HALF + n * 16) = x;
;                         u32x2 w; w.x = pk2(x.x, x.y); w.y = pk2(x.z, x.w); *(u32x2*)(xp + bj * HALF + n * 16) = w; ss += (x.x * x.x + x.y * x.y) + (x.z * x.z + x.w * x.w); }
;                 ss += __shfl_xor(ss, 16); ss += __shfl_xor(ss, 32);
;                 if (fq == 0) sred[wc * 256 + ai * HALF + wr * 64 + m * 16 + fr] = ss; }
.LBB0_730:
	s_or_b64 exec, exec, s[50:51]
	s_waitcnt lgkmcnt(0)
	v_or_b32_e32 v114, 16, v142
	v_ashrrev_i32_e32 v115, 31, v114
	v_lshlrev_b64 v[118:119], 13, v[114:115]
	v_lshl_add_u64 v[118:119], s[14:15], 0, v[118:119]
	v_lshl_add_u64 v[122:123], v[140:141], 2, v[118:119]
	s_mov_b32 s100, 0xa0000
	s_mov_b32 s101, 0
	v_lshl_add_u64 v[198:199], v[198:199], 0, s[100:101]
	global_load_dwordx4 v[210:213], v[198:199], off
	global_load_dwordx4 v[214:217], v[198:199], off offset:64
	global_load_dwordx4 v[218:221], v[198:199], off offset:512
	global_load_dwordx4 v[222:225], v[198:199], off offset:576
	v_lshlrev_b64 v[114:115], 12, v[114:115]
	v_lshl_add_u64 v[114:115], s[18:19], 0, v[114:115]
	v_lshl_add_u64 v[114:115], v[140:141], 1, v[114:115]
	s_waitcnt vmcnt(23)
	v_pk_add_f32 v[110:111], v[110:111], v[228:229]
	v_pk_add_f32 v[108:109], v[108:109], v[226:227]
	v_cvt_pk_bf16_f32 v119, v110, v111
	v_cvt_pk_bf16_f32 v118, v108, v109
	global_store_dwordx4 v[122:123], v[108:111], off
	global_store_dwordx2 v[114:115], v[118:119], off
	s_nop 0
	v_mul_f32_e32 v109, v109, v109
	v_mul_f32_e32 v111, v111, v111
	v_fmac_f32_e32 v109, v108, v108
	v_fmac_f32_e32 v111, v110, v110
	v_add_f32_e32 v108, v109, v111
	s_waitcnt vmcnt(24)
	v_pk_add_f32 v[106:107], v[106:107], v[232:233]
	v_pk_add_f32 v[104:105], v[104:105], v[230:231]
	v_cvt_pk_bf16_f32 v119, v106, v107
	v_cvt_pk_bf16_f32 v118, v104, v105
	global_store_dwordx4 v[122:123], v[104:107], off offset:64
	global_store_dwordx2 v[114:115], v[118:119], off offset:32
	s_nop 0
	v_mul_f32_e32 v105, v105, v105
	v_mul_f32_e32 v107, v107, v107
	v_fmac_f32_e32 v105, v104, v104
	v_fmac_f32_e32 v107, v106, v106
	v_add_f32_e32 v104, v105, v107
	v_add_f32_e32 v104, v108, v104
	s_waitcnt vmcnt(25)
	v_pk_add_f32 v[102:103], v[102:103], v[236:237]
	v_pk_add_f32 v[100:101], v[100:101], v[234:235]
	v_cvt_pk_bf16_f32 v119, v102, v103
	v_cvt_pk_bf16_f32 v118, v100, v101
	global_store_dwordx4 v[122:123], v[100:103], off offset:512
	global_store_dwordx2 v[114:115], v[118:119], off offset:256
	s_nop 0
	v_mul_f32_e32 v101, v101, v101
	v_mul_f32_e32 v103, v103, v103
	v_fmac_f32_e32 v101, v100, v100
	v_fmac_f32_e32 v103, v102, v102
	v_add_f32_e32 v100, v101, v103
	v_add_f32_e32 v102, v104, v100
	s_waitcnt vmcnt(26)
	v_pk_add_f32 v[100:101], v[98:99], v[240:241]
	v_pk_add_f32 v[98:99], v[96:97], v[238:239]
	v_mul_f32_e32 v97, v101, v101
	v_mul_f32_e32 v96, v99, v99
	v_fmac_f32_e32 v96, v98, v98
	v_fmac_f32_e32 v97, v100, v100
	v_add_f32_e32 v96, v96, v97
	v_add_f32_e32 v96, v102, v96
	ds_bpermute_b32 v97, v116, v96
	global_store_dwordx4 v[122:123], v[98:101], off offset:576
	s_waitcnt lgkmcnt(0)
	v_add_f32_e32 v96, v96, v97
	ds_bpermute_b32 v97, v112, v96
	v_cvt_pk_bf16_f32 v98, v98, v99
	v_cvt_pk_bf16_f32 v99, v100, v101
	global_store_dwordx2 v[114:115], v[98:99], off offset:288
	s_and_saveexec_b64 s[50:51], s[4:5]
	s_cbranch_execz .LBB0_732
	s_waitcnt lgkmcnt(0)
	v_add_f32_e32 v96, v96, v97
	ds_write_b32 v147, v96 offset:64
.LBB0_732:
	s_or_b64 exec, exec, s[50:51]
	v_or_b32_e32 v100, 32, v142
	v_ashrrev_i32_e32 v101, 31, v100
	s_waitcnt lgkmcnt(0)
	v_lshlrev_b64 v[96:97], 13, v[100:101]
	v_lshl_add_u64 v[96:97], s[14:15], 0, v[96:97]
	v_lshl_add_u64 v[102:103], v[140:141], 2, v[96:97]
	s_mov_b32 s100, 0x20000
	s_mov_b32 s101, 0
	v_lshl_add_u64 v[198:199], v[198:199], 0, s[100:101]
	global_load_dwordx4 v[226:229], v[198:199], off
	global_load_dwordx4 v[230:233], v[198:199], off offset:64
	global_load_dwordx4 v[234:237], v[198:199], off offset:512
	global_load_dwordx4 v[238:241], v[198:199], off offset:576
	v_lshlrev_b64 v[100:101], 12, v[100:101]
	v_lshl_add_u64 v[100:101], s[18:19], 0, v[100:101]
	v_lshl_add_u64 v[100:101], v[140:141], 1, v[100:101]
	s_waitcnt vmcnt(31)
	v_pk_add_f32 v[94:95], v[94:95], v[244:245]
	v_pk_add_f32 v[92:93], v[92:93], v[242:243]
	v_cvt_pk_bf16_f32 v97, v94, v95
	v_cvt_pk_bf16_f32 v96, v92, v93
	global_store_dwordx4 v[102:103], v[92:95], off
	global_store_dwordx2 v[100:101], v[96:97], off
	s_nop 0
	v_mul_f32_e32 v93, v93, v93
	v_mul_f32_e32 v95, v95, v95
	v_fmac_f32_e32 v93, v92, v92
	v_fmac_f32_e32 v95, v94, v94
	v_add_f32_e32 v92, v93, v95
	s_waitcnt vmcnt(32)
	v_pk_add_f32 v[90:91], v[90:91], v[248:249]
	v_pk_add_f32 v[88:89], v[88:89], v[246:247]
	v_cvt_pk_bf16_f32 v97, v90, v91
	v_cvt_pk_bf16_f32 v96, v88, v89
	global_store_dwordx4 v[102:103], v[88:91], off offset:64
	global_store_dwordx2 v[100:101], v[96:97], off offset:32
	s_nop 0
	v_mul_f32_e32 v89, v89, v89
	v_mul_f32_e32 v91, v91, v91
	v_fmac_f32_e32 v89, v88, v88
	v_fmac_f32_e32 v91, v90, v90
	v_add_f32_e32 v88, v89, v91
	v_add_f32_e32 v88, v92, v88
	s_waitcnt vmcnt(33)
	v_pk_add_f32 v[86:87], v[86:87], v[252:253]
	v_pk_add_f32 v[84:85], v[84:85], v[250:251]
	v_cvt_pk_bf16_f32 v97, v86, v87
	v_cvt_pk_bf16_f32 v96, v84, v85
	global_store_dwordx4 v[102:103], v[84:87], off offset:512
	global_store_dwordx2 v[100:101], v[96:97], off offset:256
	s_nop 0
	v_mul_f32_e32 v85, v85, v85
	v_mul_f32_e32 v87, v87, v87
	v_fmac_f32_e32 v85, v84, v84
	v_fmac_f32_e32 v87, v86, v86
	v_add_f32_e32 v84, v85, v87
	v_add_f32_e32 v86, v88, v84
	s_waitcnt vmcnt(34)
	v_pk_add_f32 v[84:85], v[82:83], v[170:171]
	v_pk_add_f32 v[82:83], v[80:81], v[168:169]
	v_mul_f32_e32 v81, v85, v85
	v_mul_f32_e32 v80, v83, v83
	v_fmac_f32_e32 v80, v82, v82
	v_fmac_f32_e32 v81, v84, v84
	v_add_f32_e32 v80, v80, v81
	v_add_f32_e32 v80, v86, v80
	ds_bpermute_b32 v81, v116, v80
	global_store_dwordx4 v[102:103], v[82:85], off offset:576
	s_waitcnt lgkmcnt(0)
	v_add_f32_e32 v80, v80, v81
	ds_bpermute_b32 v81, v112, v80
	v_cvt_pk_bf16_f32 v82, v82, v83
	v_cvt_pk_bf16_f32 v83, v84, v85
	global_store_dwordx2 v[100:101], v[82:83], off offset:288
	s_and_saveexec_b64 s[50:51], s[4:5]
	s_cbranch_execz .LBB0_734
	s_waitcnt lgkmcnt(0)
	v_add_f32_e32 v80, v80, v81
	ds_write_b32 v147, v80 offset:128
; __device__ __forceinline__ unsigned pk2(float lo, float hi) { f32x2_t v = {lo, hi}; bf16x2_t b = __builtin_convertvector(v, bf16x2_t); return __builtin_bit_cast(unsigned, b); }
;     __device__ __forceinline__ void operator()(const f32x4 (&acc)[2][2][4][2], const Unit& u, int wr, int wc, int fr, int fq) const {
;     ...
;             for (int m = 0; m < 4; ++m) { const int row = row0 + ai * HALF + m * 16;
;                 const float* bp = base + (size_t)row * D + col0; float* op = out + (size_t)row * D + col0; bf16_t* xp = xb + (size_t)row * D + col0;
;                 float ss = 0.f;
; #pragma unroll
;                 for (int bj = 0; bj < 2; ++bj)
; #pragma unroll
;                     for (int n = 0; n < 2; ++n) { const f32x4 b = *(const f32x4*)(bp + bj * HALF + n * 16); const f32x4 x = b + acc[ai][bj][m][n]; *(f32x4*)(op + bj * HALF + n * 16) = x;
;                         u32x2 w; w.x = pk2(x.x, x.y); w.y = pk2(x.z, x.w); *(u32x2*)(xp + bj * HALF + n * 16) = w; ss += (x.x * x.x + x.y * x.y) + (x.z * x.z + x.w * x.w); }
;                 ss += __shfl_xor(ss, 16); ss += __shfl_xor(ss, 32);
;                 if (fq == 0) sred[wc * 256 + ai * HALF + wr * 64 + m * 16 + fr] = ss; }
.LBB0_734:
	s_or_b64 exec, exec, s[50:51]
	v_or_b32_e32 v84, 48, v142
	v_ashrrev_i32_e32 v85, 31, v84
	s_waitcnt lgkmcnt(0)
	v_lshlrev_b64 v[80:81], 13, v[84:85]
	v_lshl_add_u64 v[80:81], s[14:15], 0, v[80:81]
	v_lshl_add_u64 v[86:87], v[140:141], 2, v[80:81]
	s_mov_b32 s100, 0x20000
	s_mov_b32 s101, 0
	v_lshl_add_u64 v[198:199], v[198:199], 0, s[100:101]
	global_load_dwordx4 v[242:245], v[198:199], off
	global_load_dwordx4 v[246:249], v[198:199], off offset:64
	global_load_dwordx4 v[250:253], v[198:199], off offset:512
	global_load_dwordx4 v[168:171], v[198:199], off offset:576
	v_lshlrev_b64 v[84:85], 12, v[84:85]
	v_lshl_add_u64 v[84:85], s[18:19], 0, v[84:85]
	v_lshl_add_u64 v[84:85], v[140:141], 1, v[84:85]
	s_waitcnt vmcnt(39)
	v_pk_add_f32 v[78:79], v[78:79], v[174:175]
	v_pk_add_f32 v[76:77], v[76:77], v[172:173]
	v_cvt_pk_bf16_f32 v81, v78, v79
	v_cvt_pk_bf16_f32 v80, v76, v77
	global_store_dwordx4 v[86:87], v[76:79], off
	global_store_dwordx2 v[84:85], v[80:81], off
	s_nop 0
	v_mul_f32_e32 v77, v77, v77
	v_mul_f32_e32 v79, v79, v79
	v_fmac_f32_e32 v77, v76, v76
	v_fmac_f32_e32 v79, v78, v78
	v_add_f32_e32 v76, v77, v79
	s_waitcnt vmcnt(40)
	v_pk_add_f32 v[74:75], v[74:75], v[178:179]
	v_pk_add_f32 v[72:73], v[72:73], v[176:177]
	v_cvt_pk_bf16_f32 v81, v74, v75
	v_cvt_pk_bf16_f32 v80, v72, v73
	global_store_dwordx4 v[86:87], v[72:75], off offset:64
	global_store_dwordx2 v[84:85], v[80:81], off offset:32
	s_nop 0
	v_mul_f32_e32 v73, v73, v73
	v_mul_f32_e32 v75, v75, v75
	v_fmac_f32_e32 v73, v72, v72
	v_fmac_f32_e32 v75, v74, v74
	v_add_f32_e32 v72, v73, v75
	v_add_f32_e32 v72, v76, v72
	s_waitcnt vmcnt(41)
	v_pk_add_f32 v[70:71], v[70:71], v[182:183]
	v_pk_add_f32 v[68:69], v[68:69], v[180:181]
	v_cvt_pk_bf16_f32 v81, v70, v71
	v_cvt_pk_bf16_f32 v80, v68, v69
	global_store_dwordx4 v[86:87], v[68:71], off offset:512
	global_store_dwordx2 v[84:85], v[80:81], off offset:256
	s_nop 0
	v_mul_f32_e32 v69, v69, v69
	v_mul_f32_e32 v71, v71, v71
	v_fmac_f32_e32 v69, v68, v68
	v_fmac_f32_e32 v71, v70, v70
	v_add_f32_e32 v68, v69, v71
	v_add_f32_e32 v70, v72, v68
	s_waitcnt vmcnt(42)
	v_pk_add_f32 v[68:69], v[66:67], v[186:187]
	v_pk_add_f32 v[66:67], v[64:65], v[184:185]
	v_mul_f32_e32 v65, v69, v69
	v_mul_f32_e32 v64, v67, v67
	v_fmac_f32_e32 v64, v66, v66
	v_fmac_f32_e32 v65, v68, v68
	v_add_f32_e32 v64, v64, v65
	v_add_f32_e32 v64, v70, v64
	ds_bpermute_b32 v65, v116, v64
	global_store_dwordx4 v[86:87], v[66:69], off offset:576
	s_waitcnt lgkmcnt(0)
	v_add_f32_e32 v64, v64, v65
	ds_bpermute_b32 v65, v112, v64
	v_cvt_pk_bf16_f32 v66, v66, v67
	v_cvt_pk_bf16_f32 v67, v68, v69
	global_store_dwordx2 v[84:85], v[66:67], off offset:288
	s_and_saveexec_b64 s[50:51], s[4:5]
	s_cbranch_execz .LBB0_736
	s_waitcnt lgkmcnt(0)
	v_add_f32_e32 v64, v64, v65
	ds_write_b32 v147, v64 offset:192
.LBB0_736:
	s_or_b64 exec, exec, s[50:51]
	v_add_u32_e32 v68, 0x80, v142
	v_ashrrev_i32_e32 v69, 31, v68
	s_waitcnt lgkmcnt(0)
	v_lshlrev_b64 v[64:65], 13, v[68:69]
	v_lshl_add_u64 v[64:65], s[14:15], 0, v[64:65]
	v_lshl_add_u64 v[70:71], v[140:141], 2, v[64:65]
	s_mov_b32 s100, 0x20000
	s_mov_b32 s101, 0
	v_lshl_add_u64 v[198:199], v[198:199], 0, s[100:101]
	global_load_dwordx4 v[172:175], v[198:199], off
	global_load_dwordx4 v[176:179], v[198:199], off offset:64
	global_load_dwordx4 v[180:183], v[198:199], off offset:512
	global_load_dwordx4 v[184:187], v[198:199], off offset:576
	v_lshlrev_b64 v[68:69], 12, v[68:69]
	v_lshl_add_u64 v[68:69], s[18:19], 0, v[68:69]
	v_lshl_add_u64 v[68:69], v[140:141], 1, v[68:69]
	s_waitcnt vmcnt(39)
	v_pk_add_f32 v[62:63], v[62:63], v[212:213]
	v_pk_add_f32 v[60:61], v[60:61], v[210:211]
	v_cvt_pk_bf16_f32 v65, v62, v63
	v_cvt_pk_bf16_f32 v64, v60, v61
	global_store_dwordx4 v[70:71], v[60:63], off
	global_store_dwordx2 v[68:69], v[64:65], off
	s_nop 0
	v_mul_f32_e32 v61, v61, v61
	v_mul_f32_e32 v63, v63, v63
	v_fmac_f32_e32 v61, v60, v60
	v_fmac_f32_e32 v63, v62, v62
	v_add_f32_e32 v60, v61, v63
	s_waitcnt vmcnt(40)
	v_pk_add_f32 v[58:59], v[58:59], v[216:217]
	v_pk_add_f32 v[56:57], v[56:57], v[214:215]
	v_cvt_pk_bf16_f32 v65, v58, v59
	v_cvt_pk_bf16_f32 v64, v56, v57
	global_store_dwordx4 v[70:71], v[56:59], off offset:64
	global_store_dwordx2 v[68:69], v[64:65], off offset:32
	s_nop 0
	v_mul_f32_e32 v57, v57, v57
	v_mul_f32_e32 v59, v59, v59
	v_fmac_f32_e32 v57, v56, v56
	v_fmac_f32_e32 v59, v58, v58
	v_add_f32_e32 v56, v57, v59
	v_add_f32_e32 v56, v60, v56
	s_waitcnt vmcnt(41)
	v_pk_add_f32 v[54:55], v[54:55], v[220:221]
	v_pk_add_f32 v[52:53], v[52:53], v[218:219]
	v_cvt_pk_bf16_f32 v65, v54, v55
	v_cvt_pk_bf16_f32 v64, v52, v53
	global_store_dwordx4 v[70:71], v[52:55], off offset:512
	global_store_dwordx2 v[68:69], v[64:65], off offset:256
	s_nop 0
	v_mul_f32_e32 v53, v53, v53
	v_mul_f32_e32 v55, v55, v55
	v_fmac_f32_e32 v53, v52, v52
	v_fmac_f32_e32 v55, v54, v54
	v_add_f32_e32 v52, v53, v55
	v_add_f32_e32 v54, v56, v52
	s_waitcnt vmcnt(42)
	v_pk_add_f32 v[52:53], v[50:51], v[224:225]
	v_pk_add_f32 v[50:51], v[48:49], v[222:223]
	v_mul_f32_e32 v49, v53, v53
	v_mul_f32_e32 v48, v51, v51
	v_fmac_f32_e32 v48, v50, v50
	v_fmac_f32_e32 v49, v52, v52
	v_add_f32_e32 v48, v48, v49
	v_add_f32_e32 v48, v54, v48
	ds_bpermute_b32 v49, v116, v48
	global_store_dwordx4 v[70:71], v[50:53], off offset:576
	s_waitcnt lgkmcnt(0)
	v_add_f32_e32 v48, v48, v49
	ds_bpermute_b32 v49, v112, v48
	v_cvt_pk_bf16_f32 v50, v50, v51
	v_cvt_pk_bf16_f32 v51, v52, v53
	global_store_dwordx2 v[68:69], v[50:51], off offset:288
	s_and_saveexec_b64 s[50:51], s[4:5]
	s_cbranch_execz .LBB0_738
	s_waitcnt lgkmcnt(0)
	v_add_f32_e32 v48, v48, v49
	ds_write_b32 v147, v48 offset:512
; __device__ __forceinline__ unsigned pk2(float lo, float hi) { f32x2_t v = {lo, hi}; bf16x2_t b = __builtin_convertvector(v, bf16x2_t); return __builtin_bit_cast(unsigned, b); }
;     __device__ __forceinline__ void operator()(const f32x4 (&acc)[2][2][4][2], const Unit& u, int wr, int wc, int fr, int fq) const {
;     ...
;             for (int m = 0; m < 4; ++m) { const int row = row0 + ai * HALF + m * 16;
;                 const float* bp = base + (size_t)row * D + col0; float* op = out + (size_t)row * D + col0; bf16_t* xp = xb + (size_t)row * D + col0;
;                 float ss = 0.f;
; #pragma unroll
;                 for (int bj = 0; bj < 2; ++bj)
; #pragma unroll
;                     for (int n = 0; n < 2; ++n) { const f32x4 b = *(const f32x4*)(bp + bj * HALF + n * 16); const f32x4 x = b + acc[ai][bj][m][n]; *(f32x4*)(op + bj * HALF + n * 16) = x;
;                         u32x2 w; w.x = pk2(x.x, x.y); w.y = pk2(x.z, x.w); *(u32x2*)(xp + bj * HALF + n * 16) = w; ss += (x.x * x.x + x.y * x.y) + (x.z * x.z + x.w * x.w); }
;                 ss += __shfl_xor(ss, 16); ss += __shfl_xor(ss, 32);
;                 if (fq == 0) sred[wc * 256 + ai * HALF + wr * 64 + m * 16 + fr] = ss; }
.LBB0_738:
	s_or_b64 exec, exec, s[50:51]
	v_add_u32_e32 v52, 0x90, v142
	v_ashrrev_i32_e32 v53, 31, v52
	s_waitcnt lgkmcnt(0)
	v_lshlrev_b64 v[48:49], 13, v[52:53]
	v_lshl_add_u64 v[48:49], s[14:15], 0, v[48:49]
	v_lshl_add_u64 v[54:55], v[140:141], 2, v[48:49]
	v_lshlrev_b64 v[52:53], 12, v[52:53]
	v_lshl_add_u64 v[52:53], s[18:19], 0, v[52:53]
	v_lshl_add_u64 v[52:53], v[140:141], 1, v[52:53]
	s_waitcnt vmcnt(35)
	v_pk_add_f32 v[46:47], v[46:47], v[228:229]
	v_pk_add_f32 v[44:45], v[44:45], v[226:227]
	v_cvt_pk_bf16_f32 v49, v46, v47
	v_cvt_pk_bf16_f32 v48, v44, v45
	global_store_dwordx4 v[54:55], v[44:47], off
	global_store_dwordx2 v[52:53], v[48:49], off
	s_nop 0
	v_mul_f32_e32 v45, v45, v45
	v_mul_f32_e32 v47, v47, v47
	v_fmac_f32_e32 v45, v44, v44
	v_fmac_f32_e32 v47, v46, v46
	v_add_f32_e32 v44, v45, v47
	s_waitcnt vmcnt(36)
	v_pk_add_f32 v[42:43], v[42:43], v[232:233]
	v_pk_add_f32 v[40:41], v[40:41], v[230:231]
	v_cvt_pk_bf16_f32 v49, v42, v43
	v_cvt_pk_bf16_f32 v48, v40, v41
	global_store_dwordx4 v[54:55], v[40:43], off offset:64
	global_store_dwordx2 v[52:53], v[48:49], off offset:32
	s_nop 0
	v_mul_f32_e32 v41, v41, v41
	v_mul_f32_e32 v43, v43, v43
	v_fmac_f32_e32 v41, v40, v40
	v_fmac_f32_e32 v43, v42, v42
	v_add_f32_e32 v40, v41, v43
	v_add_f32_e32 v40, v44, v40
	s_waitcnt vmcnt(37)
	v_pk_add_f32 v[38:39], v[38:39], v[236:237]
	v_pk_add_f32 v[36:37], v[36:37], v[234:235]
	v_cvt_pk_bf16_f32 v49, v38, v39
	v_cvt_pk_bf16_f32 v48, v36, v37
	global_store_dwordx4 v[54:55], v[36:39], off offset:512
	global_store_dwordx2 v[52:53], v[48:49], off offset:256
	s_nop 0
	v_mul_f32_e32 v37, v37, v37
	v_mul_f32_e32 v39, v39, v39
	v_fmac_f32_e32 v37, v36, v36
	v_fmac_f32_e32 v39, v38, v38
	v_add_f32_e32 v36, v37, v39
	v_add_f32_e32 v38, v40, v36
	s_waitcnt vmcnt(38)
	v_pk_add_f32 v[36:37], v[34:35], v[240:241]
	v_pk_add_f32 v[34:35], v[32:33], v[238:239]
	v_mul_f32_e32 v33, v37, v37
	v_mul_f32_e32 v32, v35, v35
	v_fmac_f32_e32 v32, v34, v34
	v_fmac_f32_e32 v33, v36, v36
	v_add_f32_e32 v32, v32, v33
	v_add_f32_e32 v32, v38, v32
	ds_bpermute_b32 v33, v116, v32
	global_store_dwordx4 v[54:55], v[34:37], off offset:576
	s_waitcnt lgkmcnt(0)
	v_add_f32_e32 v32, v32, v33
	ds_bpermute_b32 v33, v112, v32
	v_cvt_pk_bf16_f32 v34, v34, v35
	v_cvt_pk_bf16_f32 v35, v36, v37
	global_store_dwordx2 v[52:53], v[34:35], off offset:288
	s_and_saveexec_b64 s[50:51], s[4:5]
	s_cbranch_execz .LBB0_740
	s_waitcnt lgkmcnt(0)
	v_add_f32_e32 v32, v32, v33
	ds_write_b32 v147, v32 offset:576
; __device__ __forceinline__ unsigned pk2(float lo, float hi) { f32x2_t v = {lo, hi}; bf16x2_t b = __builtin_convertvector(v, bf16x2_t); return __builtin_bit_cast(unsigned, b); }
;     __device__ __forceinline__ void operator()(const f32x4 (&acc)[2][2][4][2], const Unit& u, int wr, int wc, int fr, int fq) const {
;     ...
;             for (int m = 0; m < 4; ++m) { const int row = row0 + ai * HALF + m * 16;
;                 const float* bp = base + (size_t)row * D + col0; float* op = out + (size_t)row * D + col0; bf16_t* xp = xb + (size_t)row * D + col0;
;                 float ss = 0.f;
; #pragma unroll
;                 for (int bj = 0; bj < 2; ++bj)
; #pragma unroll
;                     for (int n = 0; n < 2; ++n) { const f32x4 b = *(const f32x4*)(bp + bj * HALF + n * 16); const f32x4 x = b + acc[ai][bj][m][n]; *(f32x4*)(op + bj * HALF + n * 16) = x;
;                         u32x2 w; w.x = pk2(x.x, x.y); w.y = pk2(x.z, x.w); *(u32x2*)(xp + bj * HALF + n * 16) = w; ss += (x.x * x.x + x.y * x.y) + (x.z * x.z + x.w * x.w); }
;                 ss += __shfl_xor(ss, 16); ss += __shfl_xor(ss, 32);
;                 if (fq == 0) sred[wc * 256 + ai * HALF + wr * 64 + m * 16 + fr] = ss; }
.LBB0_740:
	s_or_b64 exec, exec, s[50:51]
	v_add_u32_e32 v36, 0xa0, v142
	v_ashrrev_i32_e32 v37, 31, v36
	s_waitcnt lgkmcnt(0)
	v_lshlrev_b64 v[32:33], 13, v[36:37]
	v_lshl_add_u64 v[32:33], s[14:15], 0, v[32:33]
	v_lshl_add_u64 v[38:39], v[140:141], 2, v[32:33]
	v_lshlrev_b64 v[36:37], 12, v[36:37]
	v_lshl_add_u64 v[36:37], s[18:19], 0, v[36:37]
	v_lshl_add_u64 v[36:37], v[140:141], 1, v[36:37]
	s_waitcnt vmcnt(31)
	v_pk_add_f32 v[30:31], v[30:31], v[244:245]
	v_pk_add_f32 v[28:29], v[28:29], v[242:243]
	v_cvt_pk_bf16_f32 v33, v30, v31
	v_cvt_pk_bf16_f32 v32, v28, v29
	global_store_dwordx4 v[38:39], v[28:31], off
	global_store_dwordx2 v[36:37], v[32:33], off
	s_nop 0
	v_mul_f32_e32 v29, v29, v29
	v_mul_f32_e32 v31, v31, v31
	v_fmac_f32_e32 v29, v28, v28
	v_fmac_f32_e32 v31, v30, v30
	v_add_f32_e32 v28, v29, v31
	s_waitcnt vmcnt(32)
	v_pk_add_f32 v[26:27], v[26:27], v[248:249]
	v_pk_add_f32 v[24:25], v[24:25], v[246:247]
	v_cvt_pk_bf16_f32 v33, v26, v27
	v_cvt_pk_bf16_f32 v32, v24, v25
	global_store_dwordx4 v[38:39], v[24:27], off offset:64
	global_store_dwordx2 v[36:37], v[32:33], off offset:32
	s_nop 0
	v_mul_f32_e32 v25, v25, v25
	v_mul_f32_e32 v27, v27, v27
	v_fmac_f32_e32 v25, v24, v24
	v_fmac_f32_e32 v27, v26, v26
	v_add_f32_e32 v24, v25, v27
	v_add_f32_e32 v24, v28, v24
	s_waitcnt vmcnt(33)
	v_pk_add_f32 v[22:23], v[22:23], v[252:253]
	v_pk_add_f32 v[20:21], v[20:21], v[250:251]
	v_cvt_pk_bf16_f32 v33, v22, v23
	v_cvt_pk_bf16_f32 v32, v20, v21
	global_store_dwordx4 v[38:39], v[20:23], off offset:512
	global_store_dwordx2 v[36:37], v[32:33], off offset:256
	s_nop 0
	v_mul_f32_e32 v21, v21, v21
	v_mul_f32_e32 v23, v23, v23
	v_fmac_f32_e32 v21, v20, v20
	v_fmac_f32_e32 v23, v22, v22
	v_add_f32_e32 v20, v21, v23
	v_add_f32_e32 v22, v24, v20
	s_waitcnt vmcnt(34)
	v_pk_add_f32 v[20:21], v[18:19], v[170:171]
	v_pk_add_f32 v[18:19], v[16:17], v[168:169]
	v_mul_f32_e32 v17, v21, v21
	v_mul_f32_e32 v16, v19, v19
	v_fmac_f32_e32 v16, v18, v18
	v_fmac_f32_e32 v17, v20, v20
	v_add_f32_e32 v16, v16, v17
	v_add_f32_e32 v16, v22, v16
	ds_bpermute_b32 v17, v116, v16
	global_store_dwordx4 v[38:39], v[18:21], off offset:576
	s_waitcnt lgkmcnt(0)
	v_add_f32_e32 v16, v16, v17
	ds_bpermute_b32 v17, v112, v16
	v_cvt_pk_bf16_f32 v18, v18, v19
	v_cvt_pk_bf16_f32 v19, v20, v21
	global_store_dwordx2 v[36:37], v[18:19], off offset:288
	s_and_saveexec_b64 s[50:51], s[4:5]
	s_cbranch_execz .LBB0_742
	s_waitcnt lgkmcnt(0)
	v_add_f32_e32 v16, v16, v17
	ds_write_b32 v147, v16 offset:640
.LBB0_742:
	s_or_b64 exec, exec, s[50:51]
	v_add_u32_e32 v20, 0xb0, v142
	v_ashrrev_i32_e32 v21, 31, v20
	s_waitcnt lgkmcnt(0)
	v_lshlrev_b64 v[16:17], 13, v[20:21]
	v_lshl_add_u64 v[16:17], s[14:15], 0, v[16:17]
	v_lshl_add_u64 v[22:23], v[140:141], 2, v[16:17]
	v_lshlrev_b64 v[20:21], 12, v[20:21]
	v_lshl_add_u64 v[20:21], s[18:19], 0, v[20:21]
	v_lshl_add_u64 v[20:21], v[140:141], 1, v[20:21]
	s_waitcnt vmcnt(27)
	v_pk_add_f32 v[14:15], v[14:15], v[174:175]
	v_pk_add_f32 v[12:13], v[12:13], v[172:173]
	v_cvt_pk_bf16_f32 v17, v14, v15
	v_cvt_pk_bf16_f32 v16, v12, v13
	global_store_dwordx4 v[22:23], v[12:15], off
	global_store_dwordx2 v[20:21], v[16:17], off
	s_nop 0
	v_mul_f32_e32 v13, v13, v13
	v_mul_f32_e32 v15, v15, v15
	v_fmac_f32_e32 v13, v12, v12
	v_fmac_f32_e32 v15, v14, v14
	v_add_f32_e32 v12, v13, v15
	s_waitcnt vmcnt(28)
	v_pk_add_f32 v[10:11], v[10:11], v[178:179]
	v_pk_add_f32 v[8:9], v[8:9], v[176:177]
	v_cvt_pk_bf16_f32 v17, v10, v11
	v_cvt_pk_bf16_f32 v16, v8, v9
	global_store_dwordx4 v[22:23], v[8:11], off offset:64
	global_store_dwordx2 v[20:21], v[16:17], off offset:32
	s_nop 0
	v_mul_f32_e32 v9, v9, v9
	v_mul_f32_e32 v11, v11, v11
	v_fmac_f32_e32 v9, v8, v8
	v_fmac_f32_e32 v11, v10, v10
	v_add_f32_e32 v8, v9, v11
	v_add_f32_e32 v8, v12, v8
	s_waitcnt vmcnt(29)
	v_pk_add_f32 v[6:7], v[6:7], v[182:183]
	v_pk_add_f32 v[4:5], v[4:5], v[180:181]
	v_cvt_pk_bf16_f32 v17, v6, v7
	v_cvt_pk_bf16_f32 v16, v4, v5
	global_store_dwordx4 v[22:23], v[4:7], off offset:512
	global_store_dwordx2 v[20:21], v[16:17], off offset:256
	s_nop 0
	v_mul_f32_e32 v5, v5, v5
	v_mul_f32_e32 v7, v7, v7
	v_fmac_f32_e32 v5, v4, v4
	v_fmac_f32_e32 v7, v6, v6
	v_add_f32_e32 v4, v5, v7
	v_add_f32_e32 v6, v8, v4
	s_waitcnt vmcnt(30)
	v_pk_add_f32 v[4:5], v[2:3], v[186:187]
	v_pk_add_f32 v[2:3], v[0:1], v[184:185]
	v_mul_f32_e32 v1, v5, v5
	v_mul_f32_e32 v0, v3, v3
	v_fmac_f32_e32 v0, v2, v2
	v_fmac_f32_e32 v1, v4, v4
	v_add_f32_e32 v0, v0, v1
	v_add_f32_e32 v0, v6, v0
	ds_bpermute_b32 v1, v116, v0
	global_store_dwordx4 v[22:23], v[2:5], off offset:576
	s_waitcnt lgkmcnt(0)
	v_add_f32_e32 v0, v0, v1
	ds_bpermute_b32 v1, v112, v0
	v_cvt_pk_bf16_f32 v2, v2, v3
	v_cvt_pk_bf16_f32 v3, v4, v5
	global_store_dwordx2 v[20:21], v[2:3], off offset:288
	s_and_saveexec_b64 s[50:51], s[4:5]
	s_cbranch_execz .LBB0_744
	s_waitcnt lgkmcnt(0)
	v_add_f32_e32 v0, v0, v1
	ds_write_b32 v147, v0 offset:704

; #define LAS __attribute__((address_space(3)))
; __global__ void __launch_bounds__(512, 2) mega_fwd(Args args) {
;     extern __shared__ __attribute__((aligned(16))) unsigned char lds_raw[];
;     LAS unsigned char* lds = (LAS unsigned char*)lds_raw;
;     const int tid = threadIdx.x, lane = tid & 63, wave = __builtin_amdgcn_readfirstlane(tid >> 6);
	.amdhsa_kernel _Z8mega_fwd4Args
		.amdhsa_group_segment_fixed_size 0
		.amdhsa_private_segment_fixed_size 0
		.amdhsa_kernarg_size 528
		.amdhsa_user_sgpr_count 2
		.amdhsa_user_sgpr_dispatch_ptr 0
		.amdhsa_user_sgpr_queue_ptr 0
		.amdhsa_user_sgpr_kernarg_segment_ptr 1
		.amdhsa_user_sgpr_dispatch_id 0
		.amdhsa_user_sgpr_kernarg_preload_length 0
		.amdhsa_user_sgpr_kernarg_preload_offset 0
		.amdhsa_user_sgpr_private_segment_size 0
		.amdhsa_uses_dynamic_stack 0
		.amdhsa_enable_private_segment 0
		.amdhsa_system_sgpr_workgroup_id_x 1
		.amdhsa_system_sgpr_workgroup_id_y 0
		.amdhsa_system_sgpr_workgroup_id_z 0
		.amdhsa_system_sgpr_workgroup_info 0
		.amdhsa_system_vgpr_workitem_id 2
		.amdhsa_next_free_vgpr 255
		.amdhsa_next_free_sgpr 102
		.amdhsa_accum_offset 256
		.amdhsa_reserve_vcc 1
		.amdhsa_float_round_mode_32 0
		.amdhsa_float_round_mode_16_64 0
		.amdhsa_float_denorm_mode_32 3
		.amdhsa_float_denorm_mode_16_64 3
		.amdhsa_dx10_clamp 1
		.amdhsa_ieee_mode 1
		.amdhsa_fp16_overflow 0
		.amdhsa_tg_split 0
		.amdhsa_exception_fp_ieee_invalid_op 0
		.amdhsa_exception_fp_denorm_src 0
		.amdhsa_exception_fp_ieee_div_zero 0
		.amdhsa_exception_fp_ieee_overflow 0
		.amdhsa_exception_fp_ieee_underflow 0
		.amdhsa_exception_fp_ieee_inexact 0
		.amdhsa_exception_int_div_zero 0
	.end_amdhsa_kernel

; __global__ void __launch_bounds__(512, 2) mega_fwd(Args args) {
amdhsa.kernels:
  - .agpr_count:     0
    .args:
      - .offset:         0
        .size:           272
        .value_kind:     by_value
      - .offset:         272
        .size:           4
        .value_kind:     hidden_block_count_x
      - .offset:         276
        .size:           4
        .value_kind:     hidden_block_count_y
      - .offset:         280
        .size:           4
        .value_kind:     hidden_block_count_z
      - .offset:         284
        .size:           2
        .value_kind:     hidden_group_size_x
      - .offset:         286
        .size:           2
        .value_kind:     hidden_group_size_y
      - .offset:         288
        .size:           2
        .value_kind:     hidden_group_size_z
      - .offset:         290
        .size:           2
        .value_kind:     hidden_remainder_x
      - .offset:         292
        .size:           2
        .value_kind:     hidden_remainder_y
      - .offset:         294
        .size:           2
        .value_kind:     hidden_remainder_z
      - .offset:         312
        .size:           8
        .value_kind:     hidden_global_offset_x
      - .offset:         320
        .size:           8
        .value_kind:     hidden_global_offset_y
      - .offset:         328
        .size:           8
        .value_kind:     hidden_global_offset_z
      - .offset:         336
        .size:           2
        .value_kind:     hidden_grid_dims
      - .offset:         360
        .size:           8
        .value_kind:     hidden_multigrid_sync_arg
      - .offset:         392
        .size:           4
        .value_kind:     hidden_dynamic_lds_size
    .group_segment_fixed_size: 0
    .kernarg_segment_align: 8
    .kernarg_segment_size: 528
    .language:       OpenCL C
    .language_version:
      - 2
      - 0
    .max_flat_workgroup_size: 512
    .name:           _Z8mega_fwd4Args
    .private_segment_fixed_size: 0
    .sgpr_count:     108
    .sgpr_spill_count: 11
    .symbol:         _Z8mega_fwd4Args.kd
    .uniform_work_group_size: 1
    .uses_dynamic_stack: false
    .vgpr_count:     255
    .vgpr_spill_count: 0
    .wavefront_size: 64
